# adds: scan phase co-scheduling - half of the workgroups run their sample-group units first, the other half their prompt units first
# baseline (speedup 1.0000x reference)
.LBB0_678:
	s_bfe_u32 s0, s2, 0x10003
	s_mov_b32 s1, 0
	v_writelane_b32 v255, s0, 1
	v_writelane_b32 v255, s1, 2
	v_writelane_b32 v255, s90, 8
	v_writelane_b32 v255, s90, 9
	v_writelane_b32 v255, s90, 10
	v_writelane_b32 v255, s90, 11
	s_cmp_lt_i32 s92, 4
	s_cselect_b64 s[0:1], -1, 0
	s_cmp_gt_i32 s93, 3
	s_cselect_b64 s[4:5], -1, 0
	s_and_b64 s[0:1], s[0:1], s[4:5]
	s_andn2_b64 vcc, exec, s[0:1]
	s_cbranch_vccnz .LBB0_996

.LBB0_682:
	v_readlane_b32 vcc_lo, v255, 1
	s_cmp_lg_u32 vcc_lo, 0
	s_cbranch_scc1 .LBB0_756
	v_readlane_b32 s42, v255, 8
	s_mov_b64 s[34:35], -1
	s_add_i32 s10, s42, s88
	v_writelane_b32 v255, s10, 8
	s_cmpk_gt_i32 s42, 0xff
	s_cbranch_scc1 .LBB0_681
	v_mov_b32_e32 v151, v0
	s_and_b64 vcc, exec, s[6:7]
	v_and_b32_e32 v150, 31, v151
	s_cbranch_vccz .LBB0_753
	s_mov_b64 s[44:45], 0
	s_and_b64 vcc, exec, s[8:9]
	s_mov_b64 s[34:35], 0
	s_cbranch_vccnz .LBB0_754
	v_bfe_u32 v153, v151, 5, 1
	v_lshlrev_b32_e32 v152, 2, v153
	s_and_b64 vcc, exec, s[44:45]
	s_cbranch_vccnz .LBB0_755

.LBB0_759:
	v_readlane_b32 vcc_lo, v255, 1
	s_cmp_lg_u32 vcc_lo, 0
	s_cbranch_scc1 .LBB0_865
	v_readlane_b32 s56, v255, 9
	s_mov_b64 s[0:1], -1
	s_add_i32 s6, s56, s88
	v_writelane_b32 v255, s6, 9
	s_cmpk_gt_i32 s56, 0xff
	s_cbranch_scc1 .LBB0_758
	s_ashr_i32 s48, s56, 5
	s_ashr_i32 s49, s48, 31
	s_bfe_u32 s63, s56, 0x30002
	v_mov_b32_e32 v101, v0
	s_lshl_b64 s[52:53], s[48:49], 11
	v_mov_b32_e32 v5, s53
	s_lshl_b32 s34, s63, 7
	v_cmp_lt_i32_e32 vcc, s27, v101
	s_and_saveexec_b64 s[0:1], vcc
	s_xor_b64 s[6:7], exec, s[0:1]
	s_cbranch_execz .LBB0_770
	v_cmp_lt_u32_e64 s[0:1], s50, v101
	s_and_saveexec_b64 s[8:9], s[0:1]
	s_xor_b64 s[8:9], exec, s[8:9]
	s_cbranch_execz .LBB0_767
	s_lshl_b64 s[0:1], s[48:49], 18
	s_add_u32 s0, s14, s0
	s_addc_u32 s1, s15, s1
	s_lshl_b32 s35, s34, 2
	s_add_u32 s0, s0, s35
	v_lshlrev_b32_e32 v22, 2, v101
	s_addc_u32 s1, s1, 0
	v_add_u32_e32 v2, 0xfffffd80, v22
	v_lshl_add_u64 v[6:7], v[2:3], 2, s[0:1]
	v_cmp_gt_u32_e64 s[0:1], s51, v101
	s_nop 1
	v_cndmask_b32_e64 v2, 0, v98, s[0:1]
	v_cndmask_b32_e64 v85, 0, v7, s[0:1]
	v_cndmask_b32_e64 v84, 0, v6, s[0:1]
	v_mov_b64_e32 v[14:15], v[2:3]

.LBB0_868:
	v_readlane_b32 vcc_lo, v255, 2
	s_cmp_lg_u32 vcc_lo, 0
	s_cbranch_scc1 .LBB0_877
	v_readlane_b32 s8, v255, 10
	s_mov_b64 s[6:7], -1
	s_add_i32 s9, s8, s88
	v_writelane_b32 v255, s9, 10
	s_cmpk_gt_i32 s8, 0xff
	s_cbranch_scc1 .LBB0_867
	s_and_b32 s47, s8, 1
	s_ashr_i32 s34, s8, 1
	s_lshl_b32 s8, s47, 2
	s_ashr_i32 s35, s34, 31
	s_add_i32 s45, s91, s8
	s_lshl_b32 s8, s34, 3
	v_readlane_b32 s48, v254, 9
	s_lshl_b64 s[6:7], s[34:35], 2
	s_add_i32 s34, s45, s8
	v_readlane_b32 s52, v254, 13
	v_readlane_b32 s53, v254, 14
	v_readlane_b32 s54, v254, 15
	v_readlane_b32 s55, v254, 16
	v_readlane_b32 s56, v254, 17
	v_readlane_b32 s57, v254, 18
	v_readlane_b32 s58, v254, 19
	v_readlane_b32 s59, v254, 20
	v_mov_b32_e32 v130, v0
	s_ashr_i32 s35, s34, 31
	v_readlane_b32 s60, v254, 21
	v_readlane_b32 s61, v254, 22
	v_readlane_b32 s62, v254, 23
	v_readlane_b32 s63, v254, 24
	s_mov_b64 s[52:53], s[56:57]
	s_lshl_b64 s[8:9], s[34:35], 14
	v_bfe_u32 v131, v130, 5, 1
	s_lshl_b64 s[34:35], s[34:35], 16
	s_mov_b64 s[54:55], s[58:59]
	s_add_u32 s34, s54, s34
	v_or_b32_e32 v2, s3, v131
	v_lshlrev_b32_e32 v132, 2, v130
	s_addc_u32 s35, s55, s35
	v_lshlrev_b32_e32 v134, 9, v2
	v_and_b32_e32 v138, 0x7c, v132
	v_lshlrev_b32_e32 v136, 7, v2
	v_lshl_add_u64 v[2:3], s[34:35], 0, v[134:135]
	v_lshlrev_b32_e32 v134, 2, v138
	s_waitcnt vmcnt(2)
	v_lshl_add_u64 v[106:107], v[2:3], 0, v[134:135]
	v_lshl_add_u32 v18, s47, 9, v130
	v_add_co_u32_e32 v26, vcc, s37, v106
	v_ashrrev_i32_e32 v19, 31, v18
	s_nop 0
	v_addc_co_u32_e32 v27, vcc, 0, v107, vcc
	v_lshl_add_u64 v[20:21], v[18:19], 2, s[18:19]
	v_add_co_u32_e32 v22, vcc, s37, v20
	global_load_dwordx4 v[14:17], v[106:107], off nt
	global_load_dwordx4 v[10:13], v[106:107], off offset:1024 nt
	global_load_dwordx4 v[6:9], v[106:107], off offset:2048 nt
	global_load_dwordx4 v[2:5], v[106:107], off offset:3072 nt
	v_addc_co_u32_e32 v23, vcc, 0, v21, vcc
	global_load_dword v116, v[22:23], off
	global_load_dword v117, v[20:21], off
	s_add_u32 s6, s6, 0x4000
	s_addc_u32 s7, s7, 0
	s_lshl_b64 s[34:35], s[6:7], 11
	v_readlane_b32 s49, v254, 10
	s_add_u32 s48, s28, s34
	s_addc_u32 s49, s29, s35
	v_lshlrev_b64 v[30:31], 1, v[18:19]
	v_lshl_add_u64 v[32:33], s[48:49], 0, v[30:31]
	global_load_ushort v118, v[32:33], off
	global_load_dwordx4 v[22:25], v[26:27], off offset:1024 nt
	global_load_dwordx4 v[18:21], v[26:27], off offset:2048 nt
	s_add_u32 s48, s12, s34
	s_addc_u32 s49, s13, s35
	v_lshl_add_u64 v[90:91], s[48:49], 0, v[30:31]
	global_load_ushort v133, v[90:91], off
	v_add_co_u32_e32 v28, vcc, s38, v106
	s_add_u32 s34, s30, s34
	s_nop 0
	v_addc_co_u32_e32 v29, vcc, 0, v107, vcc
	s_addc_u32 s35, s31, s35
	v_lshl_add_u64 v[92:93], s[34:35], 0, v[30:31]
	v_add_co_u32_e32 v30, vcc, s37, v32
	v_and_b32_e32 v157, 0x7f, v130
	s_nop 0
	v_addc_co_u32_e32 v31, vcc, 0, v33, vcc
	global_load_ushort v134, v[92:93], off
	global_load_ushort v140, v[92:93], off offset:2048
	global_load_ushort v141, v[30:31], off
	global_load_ushort v142, v[30:31], off offset:2048
	global_load_ushort v143, v[90:91], off offset:2048
	global_load_ushort v145, v[32:33], off offset:2048
	global_load_dwordx4 v[78:81], v[28:29], off offset:-4096 nt
	global_load_dwordx4 v[74:77], v[28:29], off nt
	global_load_dwordx4 v[70:73], v[28:29], off offset:1024 nt
	global_load_dwordx4 v[66:69], v[28:29], off offset:2048 nt
	v_add_co_u32_e32 v30, vcc, s39, v106
	v_and_or_b32 v132, v132, s44, v157
	s_nop 0
	v_addc_co_u32_e32 v31, vcc, 0, v107, vcc
	v_add_co_u32_e32 v32, vcc, s40, v106
	v_lshl_add_u32 v132, v132, 2, 0
	s_nop 0
	v_addc_co_u32_e32 v33, vcc, 0, v107, vcc
	v_add_co_u32_e32 v108, vcc, s41, v106
	global_load_dwordx4 v[82:85], v[28:29], off offset:3072 nt
	global_load_dwordx4 v[34:37], v[32:33], off offset:-4096 nt
	global_load_dwordx4 v[86:89], v[26:27], off offset:3072 nt
	global_load_dwordx4 v[62:65], v[30:31], off offset:1024 nt
	global_load_dwordx4 v[58:61], v[30:31], off offset:2048 nt
	global_load_dwordx4 v[54:57], v[30:31], off offset:3072 nt
	global_load_dwordx4 v[50:53], v[32:33], off nt
	global_load_dwordx4 v[46:49], v[32:33], off offset:1024 nt
	global_load_dwordx4 v[42:45], v[32:33], off offset:2048 nt
	global_load_dwordx4 v[38:41], v[32:33], off offset:3072 nt
	v_addc_co_u32_e32 v109, vcc, 0, v107, vcc
	v_add_co_u32_e32 v90, vcc, s37, v90
	v_and_b32_e32 v144, 63, v130
	s_nop 0
	v_addc_co_u32_e32 v91, vcc, 0, v91, vcc
	s_waitcnt vmcnt(30)
	v_add_co_u32_e32 v114, vcc, s25, v106
	global_load_ushort v146, v[90:91], off
	s_nop 0
	v_addc_co_u32_e32 v115, vcc, 0, v107, vcc
	v_add_co_u32_e32 v92, vcc, s37, v92
	global_load_dwordx4 v[30:33], v[108:109], off offset:1024 nt
	global_load_dwordx4 v[26:29], v[108:109], off offset:2048 nt
	v_addc_co_u32_e32 v93, vcc, 0, v93, vcc
	global_load_ushort v147, v[92:93], off
	global_load_ushort v148, v[92:93], off offset:2048
	global_load_ushort v149, v[90:91], off offset:2048
	global_load_dwordx4 v[110:113], v[114:115], off offset:-4096 nt
	global_load_dwordx4 v[102:105], v[114:115], off nt
	global_load_dwordx4 v[98:101], v[114:115], off offset:1024 nt
	global_load_dwordx4 v[94:97], v[114:115], off offset:2048 nt
	s_nop 0
	global_load_dwordx4 v[90:93], v[114:115], off offset:3072 nt
	v_lshlrev_b32_e32 v130, 4, v130
	v_and_b32_e32 v130, 0x1f0, v130
	s_mov_b32 s46, 0
	v_readlane_b32 s50, v254, 11
	v_readlane_b32 s51, v254, 12
	s_mov_b64 s[56:57], s[60:61]
	s_mov_b64 s[58:59], s[62:63]
	s_waitcnt vmcnt(35)
	v_sub_f32_e32 v114, v116, v117
	v_mul_f32_e32 v114, 0x3fb8aa3b, v114
	v_exp_f32_e32 v116, v114
	v_add_co_u32_e32 v114, vcc, s42, v106
	v_add_f32_e32 v116, 1.0, v116
	v_rcp_f32_e32 v150, v116
	s_waitcnt vmcnt(34)
	v_lshlrev_b32_e32 v116, 16, v118
	v_max_f32_e32 v116, v116, v116
	v_med3_f32 v116, v116, s43, v139
	v_addc_co_u32_e32 v115, vcc, 0, v107, vcc
	v_mul_f32_e32 v116, 0xbfb8aa3b, v116
	global_load_dwordx4 v[126:129], v[108:109], off offset:3072 nt
	s_nop 0
	global_load_dwordx4 v[106:109], v[114:115], off nt
	v_exp_f32_e32 v151, v116
	global_load_dwordx4 v[122:125], v[114:115], off offset:1024 nt
	global_load_dwordx4 v[118:121], v[114:115], off offset:2048 nt
	s_nop 0
	global_load_dwordx4 v[114:117], v[114:115], off offset:3072 nt
	s_waitcnt vmcnt(36)
	v_lshlrev_b32_e32 v133, 16, v133
	v_mul_f32_e32 v153, 0xbfb8aa3b, v133
	v_exp_f32_e32 v153, v153
	v_add_f32_e32 v151, 1.0, v151
	s_waitcnt vmcnt(31)
	v_lshlrev_b32_e32 v143, 16, v143
	s_waitcnt vmcnt(30)
	v_lshlrev_b32_e32 v145, 16, v145
	v_max_f32_e32 v145, v145, v145
	v_med3_f32 v145, v145, s43, v139
	v_mul_f32_e32 v145, 0xbfb8aa3b, v145
	v_add_f32_e32 v153, 1.0, v153
	v_exp_f32_e32 v145, v145
	v_rcp_f32_e32 v153, v153
	v_lshlrev_b32_e32 v141, 16, v141
	v_rcp_f32_e32 v151, v151
	v_add_f32_e32 v145, 1.0, v145
	v_mul_f32_e32 v133, v153, v133
	v_rcp_f32_e32 v145, v145
	v_mul_f32_e32 v153, 0xbfb8aa3b, v143
	v_max_f32_e32 v141, v141, v141
	v_exp_f32_e32 v153, v153
	v_med3_f32 v141, v141, s43, v139
	v_mul_f32_e32 v141, 0xbfb8aa3b, v141
	v_sub_f32_e32 v152, 1.0, v150
	v_exp_f32_e32 v141, v141
	v_fma_f32 v151, v152, v151, v150
	v_fma_f32 v145, v152, v145, v150
	v_sub_f32_e32 v157, 1.0, v151
	ds_write2st64_b32 v132, v151, v145 offset1:2
	v_add_f32_e32 v151, 1.0, v153
	v_rcp_f32_e32 v151, v151
	v_add_f32_e32 v141, 1.0, v141
	v_rcp_f32_e32 v141, v141
	v_lshlrev_b32_e32 v134, 16, v134
	v_mul_f32_e32 v143, v151, v143
	ds_write2st64_b32 v132, v133, v143 offset0:64 offset1:66
	v_lshlrev_b32_e32 v133, 16, v140
	ds_write2st64_b32 v132, v134, v133 offset0:96 offset1:98
	v_fma_f32 v133, v152, v141, v150
	v_lshlrev_b32_e32 v141, 16, v142
	v_max_f32_e32 v141, v141, v141
	v_med3_f32 v141, v141, s43, v139
	v_mul_f32_e32 v141, 0xbfb8aa3b, v141
	v_exp_f32_e32 v141, v141
	v_sub_f32_e32 v145, 1.0, v145
	s_waitcnt vmcnt(15)
	v_lshlrev_b32_e32 v134, 16, v146
	s_waitcnt vmcnt(10)
	v_lshlrev_b32_e32 v143, 16, v149
	ds_write2st64_b32 v132, v157, v145 offset0:32 offset1:34
	v_mul_f32_e32 v140, 0xbfb8aa3b, v134
	v_add_f32_e32 v141, 1.0, v141
	v_mul_f32_e32 v145, 0xbfb8aa3b, v143
	v_exp_f32_e32 v140, v140
	v_rcp_f32_e32 v141, v141
	v_exp_f32_e32 v145, v145
	v_sub_f32_e32 v142, 1.0, v133
	v_add_f32_e32 v140, 1.0, v140
	v_fmac_f32_e32 v150, v152, v141
	v_add_f32_e32 v141, 1.0, v145
	v_rcp_f32_e32 v140, v140
	v_rcp_f32_e32 v141, v141
	ds_write2st64_b32 v132, v133, v150 offset0:4 offset1:6
	v_sub_f32_e32 v133, 1.0, v150
	v_mul_f32_e32 v134, v140, v134
	ds_write2st64_b32 v132, v142, v133 offset0:36 offset1:38
	v_mul_f32_e32 v133, v141, v143
	v_lshlrev_b32_e32 v140, 16, v147
	ds_write2st64_b32 v132, v134, v133 offset0:68 offset1:70
	v_lshlrev_b32_e32 v133, 16, v148
	v_cmp_lt_i32_e32 vcc, v155, v156
	ds_write2st64_b32 v132, v140, v133 offset0:100 offset1:102
	v_add_u32_e32 v134, s24, v130
	v_cndmask_b32_e32 v132, v154, v155, vcc
	v_add_u32_e32 v146, s26, v130
	v_add_u32_e32 v130, s27, v131
	v_lshlrev_b32_e32 v145, 2, v132
	v_cmp_gt_u32_e32 vcc, 32, v144
	v_lshl_add_u32 v147, v130, 2, 0
	s_waitcnt lgkmcnt(0)
	s_barrier
	s_branch .LBB0_875

.LBB0_881:
	v_readlane_b32 vcc_lo, v255, 2
	s_cmp_lg_u32 vcc_lo, 0
	s_cbranch_scc1 .LBB0_942
	v_readlane_b32 s69, v255, 11
	s_mov_b64 s[0:1], -1
	s_add_i32 s4, s69, s88
	v_writelane_b32 v255, s4, 11
	s_cmpk_gt_i32 s69, 0x287
	s_cbranch_scc1 .LBB0_880
	s_cmpk_lt_i32 s69, 0x200
	s_cbranch_scc0 .LBB0_932
	s_and_b32 s15, s69, 3
	s_ashr_i32 s36, s69, 2
	s_lshl_b32 s10, s15, 3
	s_add_i32 s14, s33, s10
	s_lshl_b32 s0, s36, 5
	s_add_i32 s0, s14, s0
	s_ashr_i32 s37, s36, 31
	s_ashr_i32 s1, s0, 31
	v_readlane_b32 s52, v254, 9
	s_waitcnt vmcnt(4)
	v_mov_b32_e32 v164, v0
	s_lshl_b64 s[4:5], s[36:37], 2
	s_lshl_b64 s[6:7], s[0:1], 15
	v_readlane_b32 s58, v254, 15
	v_readlane_b32 s59, v254, 16
	v_bfe_u32 v167, v164, 5, 1
	s_add_u32 s6, s58, s6
	v_and_b32_e32 v168, 31, v164
	s_addc_u32 s7, s59, s7
	v_lshlrev_b32_e32 v140, 9, v167
	v_lshl_add_u64 v[2:3], s[6:7], 0, v[140:141]
	v_lshlrev_b32_e32 v140, 4, v168
	v_lshl_add_u64 v[94:95], v[2:3], 0, v[140:141]
	v_add_co_u32_e32 v2, vcc, s47, v94
	s_movk_i32 s6, 0x7000
	s_nop 0
	v_addc_co_u32_e32 v3, vcc, 0, v95, vcc
	s_waitcnt vmcnt(1)
	v_add_co_u32_e32 v110, vcc, s48, v94
	global_load_dwordx4 v[90:93], v[94:95], off nt
	global_load_dwordx4 v[86:89], v[94:95], off offset:1024 nt
	global_load_dwordx4 v[82:85], v[94:95], off offset:2048 nt
	global_load_dwordx4 v[78:81], v[94:95], off offset:3072 nt
	v_addc_co_u32_e32 v111, vcc, 0, v95, vcc
	v_add_co_u32_e32 v4, vcc, s49, v94
	global_load_dwordx4 v[74:77], v[2:3], off offset:1024 nt
	global_load_dwordx4 v[70:73], v[2:3], off offset:2048 nt
	global_load_dwordx4 v[66:69], v[110:111], off nt
	global_load_dwordx4 v[62:65], v[110:111], off offset:1024 nt
	global_load_dwordx4 v[58:61], v[110:111], off offset:2048 nt
	global_load_dwordx4 v[54:57], v[110:111], off offset:3072 nt
	v_addc_co_u32_e32 v5, vcc, 0, v95, vcc
	v_add_co_u32_e32 v6, vcc, s50, v94
	s_add_u32 s8, s4, 0x4000
	s_nop 0
	v_addc_co_u32_e32 v7, vcc, 0, v95, vcc
	v_add_co_u32_e32 v96, vcc, s51, v94
	global_load_dwordx4 v[122:125], v[2:3], off offset:3072 nt
	global_load_dwordx4 v[26:29], v[4:5], off offset:1024 nt
	global_load_dwordx4 v[22:25], v[4:5], off offset:2048 nt
	global_load_dwordx4 v[18:21], v[4:5], off offset:3072 nt
	global_load_dwordx4 v[106:109], v[6:7], off offset:-4096 nt
	global_load_dwordx4 v[50:53], v[6:7], off nt
	global_load_dwordx4 v[46:49], v[6:7], off offset:1024 nt
	global_load_dwordx4 v[42:45], v[6:7], off offset:2048 nt
	v_addc_co_u32_e32 v97, vcc, 0, v95, vcc
	s_waitcnt vmcnt(18)
	v_add_co_u32_e32 v38, vcc, s24, v94
	s_movk_i32 s4, 0x17f
	s_nop 0
	v_addc_co_u32_e32 v39, vcc, 0, v95, vcc
	global_load_dwordx4 v[114:117], v[6:7], off offset:3072 nt
	global_load_dwordx4 v[14:17], v[38:39], off offset:-4096 nt
	global_load_dwordx4 v[10:13], v[96:97], off offset:1024 nt
	s_nop 0
	global_load_dwordx4 v[6:9], v[96:97], off offset:2048 nt
	global_load_dwordx4 v[2:5], v[38:39], off nt
	global_load_dwordx4 v[30:33], v[38:39], off offset:1024 nt
	global_load_dwordx4 v[34:37], v[38:39], off offset:2048 nt
	s_nop 0
	global_load_dwordx4 v[38:41], v[38:39], off offset:3072 nt
	v_add_co_u32_e32 v112, vcc, s6, v94
	s_addc_u32 s9, s5, 0
	s_nop 0
	v_addc_co_u32_e32 v113, vcc, 0, v95, vcc
	global_load_dwordx4 v[118:121], v[96:97], off offset:3072 nt
	s_nop 0
	global_load_dwordx4 v[94:97], v[112:113], off nt
	global_load_dwordx4 v[98:101], v[112:113], off offset:1024 nt
	global_load_dwordx4 v[102:105], v[112:113], off offset:2048 nt
	global_load_dwordx4 v[126:129], v[110:111], off offset:-4096 nt
	s_nop 0
	global_load_dwordx4 v[110:113], v[112:113], off offset:3072 nt
	v_cmp_lt_i32_e32 vcc, s4, v164
	v_readlane_b32 s53, v254, 10
	v_readlane_b32 s54, v254, 11
	v_readlane_b32 s55, v254, 12
	v_readlane_b32 s56, v254, 13
	v_readlane_b32 s57, v254, 14
	v_readlane_b32 s60, v254, 17
	v_readlane_b32 s61, v254, 18
	v_readlane_b32 s62, v254, 19
	v_readlane_b32 s63, v254, 20
	v_readlane_b32 s64, v254, 21
	v_readlane_b32 s65, v254, 22
	v_readlane_b32 s66, v254, 23
	v_readlane_b32 s67, v254, 24
	s_and_saveexec_b64 s[4:5], vcc
	s_xor_b64 s[4:5], exec, s[4:5]
	s_cbranch_execz .LBB0_893
	s_movk_i32 s6, 0x1a0
	v_cmp_gt_u32_e32 vcc, s6, v164
	s_and_saveexec_b64 s[6:7], vcc
	s_cbranch_execz .LBB0_892
	v_and_or_b32 v130, v164, 3, s8
	v_mov_b32_e32 v131, s9
	v_lshlrev_b64 v[130:131], 7, v[130:131]
	v_add_u32_e32 v132, 0xfffffe80, v164
	v_lshl_add_u64 v[130:131], s[20:21], 0, v[130:131]
	s_lshl_b32 s18, s10, 2
	v_lshrrev_b32_e32 v133, 2, v132
	v_and_b32_e32 v140, -4, v132
	v_lshl_add_u64 v[130:131], v[130:131], 0, s[18:19]
	v_lshl_add_u64 v[130:131], v[130:131], 0, v[140:141]
	v_add_u32_e32 v140, s10, v133
	global_load_dword v132, v[130:131], off
	v_lshl_add_u64 v[130:131], v[140:141], 2, s[76:77]
	global_load_dword v130, v[130:131], off
	s_mov_b32 s10, 0x41a00000
	s_waitcnt vmcnt(0)
	v_add_f32_e32 v130, v132, v130
	v_cmp_nlt_f32_e32 vcc, s10, v130
	s_and_saveexec_b64 s[10:11], vcc
	s_cbranch_execz .LBB0_891
	v_mul_f32_e32 v130, 0x3fb8aa3b, v130
	v_exp_f32_e32 v139, v130
	s_mov_b32 s12, 0x3f2aaaab
	v_add_f32_e32 v132, 1.0, v139
	v_frexp_mant_f32_e32 v134, v132
	v_cvt_f64_f32_e32 v[130:131], v132
	v_frexp_exp_i32_f64_e32 v130, v[130:131]
	v_cmp_gt_f32_e32 vcc, s12, v134
	v_add_f32_e32 v133, -1.0, v132
	v_sub_f32_e32 v135, v133, v132
	v_subbrev_co_u32_e32 v140, vcc, 0, v130, vcc
	v_sub_u32_e32 v130, 0, v140
	v_sub_f32_e32 v133, v139, v133
	v_add_f32_e32 v135, 1.0, v135
	v_ldexp_f32 v131, v132, v130
	v_add_f32_e32 v133, v133, v135
	v_add_f32_e32 v132, -1.0, v131
	v_add_f32_e32 v134, 1.0, v131
	v_ldexp_f32 v130, v133, v130
	v_add_f32_e32 v133, 1.0, v132
	v_add_f32_e32 v135, -1.0, v134
	v_sub_f32_e32 v133, v131, v133
	v_sub_f32_e32 v131, v131, v135
	v_add_f32_e32 v133, v130, v133
	v_add_f32_e32 v130, v130, v131
	v_add_f32_e32 v143, v134, v130
	v_rcp_f32_e32 v145, v143
	v_sub_f32_e32 v131, v143, v134
	v_sub_f32_e32 v144, v130, v131
	v_add_f32_e32 v131, v132, v133
	v_mul_f32_e32 v147, v131, v145
	v_sub_f32_e32 v130, v131, v132
	v_mul_f32_e32 v132, v143, v147
	v_fma_f32 v134, v147, v143, -v132
	v_fmac_f32_e32 v134, v147, v144
	v_sub_f32_e32 v146, v133, v130
	v_add_f32_e32 v130, v132, v134
	v_sub_f32_e32 v133, v131, v130
	v_pk_add_f32 v[136:137], v[130:131], v[132:133] neg_lo:[0,1] neg_hi:[0,1]
	v_mov_b32_e32 v135, v130
	v_pk_add_f32 v[130:131], v[136:137], v[134:135] neg_lo:[0,1] neg_hi:[0,1]
	s_mov_b32 s12, 0x3f317218
	v_add_f32_e32 v131, v146, v131
	v_add_f32_e32 v130, v130, v131
	v_add_f32_e32 v131, v133, v130
	v_mul_f32_e32 v146, v145, v131
	v_mul_f32_e32 v132, v143, v146
	v_fma_f32 v134, v146, v143, -v132
	v_fmac_f32_e32 v134, v146, v144
	v_sub_f32_e32 v133, v133, v131
	v_add_f32_e32 v143, v130, v133
	v_add_f32_e32 v130, v132, v134
	v_sub_f32_e32 v133, v131, v130
	v_pk_add_f32 v[136:137], v[130:131], v[132:133] neg_lo:[0,1] neg_hi:[0,1]
	v_mov_b32_e32 v135, v130
	v_pk_add_f32 v[130:131], v[136:137], v[134:135] neg_lo:[0,1] neg_hi:[0,1]
	s_nop 0
	v_add_f32_e32 v131, v143, v131
	v_add_f32_e32 v130, v130, v131
	v_add_f32_e32 v131, v147, v146
	v_add_f32_e32 v130, v133, v130
	v_sub_f32_e32 v132, v131, v147
	v_mul_f32_e32 v130, v145, v130
	v_sub_f32_e32 v132, v146, v132
	v_add_f32_e32 v132, v132, v130
	v_add_f32_e32 v134, v131, v132
	v_mul_f32_e32 v135, v134, v134
	v_fmamk_f32 v130, v135, 0x3e9b6dac, v158
	v_fmaak_f32 v143, v135, v130, 0x3f2aaada
	v_cvt_f32_i32_e32 v130, v140
	v_sub_f32_e32 v131, v134, v131
	v_sub_f32_e32 v131, v132, v131
	v_ldexp_f32 v136, v131, 1
	v_mul_f32_e32 v131, v134, v135
	v_ldexp_f32 v133, v134, 1
	v_pk_mul_f32 v[134:135], v[130:131], v[142:143]
	s_nop 0
	v_fma_f32 v132, v130, s12, -v134
	v_fmac_f32_e32 v132, 0xb102e308, v130
	v_pk_add_f32 v[130:131], v[134:135], v[132:133]
	s_mov_b32 s12, 0x7f800000
	v_sub_f32_e32 v133, v131, v133
	v_sub_f32_e32 v133, v135, v133
	v_add_f32_e32 v137, v136, v133
	v_mov_b32_e32 v136, v134
	v_pk_add_f32 v[134:135], v[130:131], v[134:135] neg_lo:[0,1] neg_hi:[0,1]
	v_pk_add_f32 v[144:145], v[130:131], v[136:137]
	v_mov_b32_e32 v133, v130
	v_mov_b32_e32 v135, v145
	v_pk_add_f32 v[146:147], v[132:133], v[134:135] neg_lo:[0,1] neg_hi:[0,1]
	v_pk_add_f32 v[132:133], v[132:133], v[134:135]
	v_mov_b32_e32 v136, v137
	v_pk_add_f32 v[134:135], v[132:133], v[130:131] op_sel:[1,0] op_sel_hi:[0,1] neg_lo:[0,1] neg_hi:[0,1]
	v_pk_add_f32 v[148:149], v[144:145], v[134:135] op_sel_hi:[1,0] neg_lo:[0,1] neg_hi:[0,1]
	v_mov_b32_e32 v144, v145
	v_mov_b32_e32 v145, v133
	v_pk_mov_b32 v[134:135], v[130:131], v[134:135] op_sel:[1,0]
	v_mov_b32_e32 v137, v130
	v_pk_add_f32 v[134:135], v[144:145], v[134:135] neg_lo:[0,1] neg_hi:[0,1]
	v_mov_b32_e32 v148, v146
	v_pk_add_f32 v[130:131], v[136:137], v[134:135] neg_lo:[0,1] neg_hi:[0,1]
	v_mov_b32_e32 v147, v133
	v_pk_add_f32 v[134:135], v[148:149], v[130:131]
	v_cmp_neq_f32_e32 vcc, s12, v139
	v_pk_add_f32 v[136:137], v[134:135], v[134:135] op_sel:[0,1] op_sel_hi:[1,0]
	s_mov_b32 s12, 0x33800000
	v_pk_add_f32 v[132:133], v[132:133], v[136:137] op_sel:[1,0] op_sel_hi:[0,1]
	v_mov_b32_e32 v135, v132
	v_pk_add_f32 v[144:145], v[134:135], v[146:147] neg_lo:[0,1] neg_hi:[0,1]
	v_mov_b32_e32 v131, v136
	v_sub_f32_e32 v133, v134, v144
	v_pk_add_f32 v[130:131], v[130:131], v[144:145] neg_lo:[0,1] neg_hi:[0,1]
	v_sub_f32_e32 v133, v146, v133
	v_add_f32_e32 v130, v130, v133
	v_add_f32_e32 v130, v130, v131
	v_add_f32_e32 v130, v132, v130
	v_cndmask_b32_e32 v130, v159, v130, vcc
	v_cmp_ngt_f32_e32 vcc, -1.0, v139
	s_nop 1
	v_cndmask_b32_e32 v130, v160, v130, vcc
	v_cmp_neq_f32_e32 vcc, -1.0, v139
	s_nop 1
	v_cndmask_b32_e32 v130, v161, v130, vcc
	v_cmp_lt_f32_e64 vcc, |v139|, s12
	s_nop 1
	v_cndmask_b32_e32 v130, v130, v139, vcc
